# speedup vs baseline: 1.0115x; 1.0008x over previous
; #define WAIT_V(n) asm volatile("s_waitcnt vmcnt(" #n ")" ::: "memory")
; #define BAR __builtin_amdgcn_s_barrier()
; __device__ __forceinline__ void gemm_run(const Params& p, const u16* A1, const u16* Bt1, int M1, int N1, int K, int mode1,
;                                          const float* resid, u16* shm, const u16* A2, const u16* Bt2, int M2, int N2,
;                                          int mode2) {
;     ...
;     f32x4 acc[2][2][4][2] = {};
;     bf16x8 At[4][2], B0[2][2], B1[2][2];
;     STAGE(SB(0, 0), Bt, bcol, 0); STAGE(SA(0, 0), A, brow, 0);
;     STAGE(SB(0, 1), Bt, bcol + HALF, 0); STAGE(SA(0, 1), A, brow + HALF, 0);
;     if (wr == 1) BAR;
;     WAIT_V(4); BAR;
;     STAGE(SB(1, 0), Bt, bcol, 1); STAGE(SA(1, 0), A, brow, 1); STAGE(SB(1, 1), Bt, bcol + HALF, 1);
;     WAIT_V(6); BAR;
.LBB0_396:
	s_ashr_i32 s76, s91, 31
	s_mul_hi_u32 s0, s91, s96
	s_mul_i32 s2, s76, s96
	s_add_i32 s1, s0, s2
	s_mul_i32 s0, s91, s96
	s_lshl_b64 s[0:1], s[0:1], 1
	s_add_u32 s10, s56, s0
	s_addc_u32 s11, s57, s1
	s_mov_b32 s0, m0
	s_mov_b32 m0, s67
	s_nop 0
	global_load_lds_dwordx4 v135, s[10:11]
	s_mov_b32 m0, s0
	s_ashr_i32 s77, s74, 31
	s_mov_b32 s0, m0
	s_mov_b32 m0, s68
	s_nop 0
	global_load_lds_dwordx4 v182, s[10:11]
	s_mov_b32 m0, s0
	s_mul_hi_u32 s0, s74, s96
	s_mul_i32 s3, s77, s96
	s_add_i32 s1, s0, s3
	s_mul_i32 s0, s74, s96
	s_lshl_b64 s[0:1], s[0:1], 1
	s_add_u32 s12, s14, s0
	s_addc_u32 s13, s15, s1
	s_mov_b32 s0, m0
	s_mov_b32 m0, s65
	s_nop 0
	global_load_lds_dwordx4 v135, s[12:13]
	s_mov_b32 m0, s0
	s_nop 0
	s_mov_b32 s0, m0
	s_mov_b32 m0, s69
	s_nop 0
	global_load_lds_dwordx4 v182, s[12:13]
	s_mov_b32 m0, s0
	s_or_b32 s0, s91, 0x80
	s_mul_hi_u32 s1, s0, s96
	s_add_i32 s1, s1, s2
	s_mul_i32 s0, s0, s96
	s_lshl_b64 s[0:1], s[0:1], 1
	s_add_u32 s0, s56, s0
	s_addc_u32 s1, s57, s1
	s_mov_b32 s2, m0
	s_mov_b32 m0, s70
	s_nop 0
	global_load_lds_dwordx4 v135, s[0:1]
	s_mov_b32 m0, s2
	s_nop 0
	s_mov_b32 s2, m0
	s_mov_b32 m0, s71
	s_nop 0
	global_load_lds_dwordx4 v182, s[0:1]
	s_mov_b32 m0, s2
	s_or_b32 s2, s74, 0x80
	s_mul_hi_u32 s8, s2, s96
	s_add_i32 s3, s8, s3
	s_mul_i32 s2, s2, s96
	s_lshl_b64 s[2:3], s[2:3], 1
	s_add_u32 s8, s14, s2
	s_addc_u32 s9, s15, s3
	s_mov_b32 s2, m0
	s_mov_b32 m0, s72
	s_nop 0
	global_load_lds_dwordx4 v135, s[8:9]
	s_mov_b32 m0, s2
	s_nop 0
	s_mov_b32 s2, m0
	s_mov_b32 m0, s73
	s_nop 0
	global_load_lds_dwordx4 v182, s[8:9]
	s_mov_b32 m0, s2
	s_add_u32 s2, s10, 0x80
	s_addc_u32 s3, s11, 0
	s_mov_b32 s75, m0
	s_mov_b32 m0, s78
	s_nop 0
	global_load_lds_dwordx4 v135, s[2:3]
	s_mov_b32 m0, s75
	s_mov_b32 s75, m0
	s_mov_b32 m0, s79
	s_nop 0
	global_load_lds_dwordx4 v182, s[2:3]
	s_mov_b32 m0, s75
	s_add_u32 s2, s12, 0x80
	s_addc_u32 s3, s13, 0
	s_mov_b32 s75, m0
	s_mov_b32 m0, s80
	s_nop 0
	global_load_lds_dwordx4 v135, s[2:3]
	s_mov_b32 m0, s75
	s_mov_b32 s75, m0
	s_mov_b32 m0, s81
	s_nop 0
	global_load_lds_dwordx4 v182, s[2:3]
	s_mov_b32 m0, s75
	s_add_u32 s0, s0, 0x80
	s_addc_u32 s1, s1, 0
	s_mov_b32 s2, m0
	s_mov_b32 m0, s82
	s_nop 0
	global_load_lds_dwordx4 v135, s[0:1]
	s_mov_b32 m0, s2
	s_mov_b32 s2, m0
	s_mov_b32 m0, s83
	s_nop 0
	global_load_lds_dwordx4 v182, s[0:1]
	s_mov_b32 m0, s2
	v_mov_b32_e32 v125, 0
	v_mov_b32_e32 v2, v125
	v_mov_b32_e32 v3, v125
	v_mov_b32_e32 v4, v125
	v_mov_b32_e32 v5, v125
	v_mov_b32_e32 v6, v125
	v_mov_b32_e32 v7, v125
	v_mov_b32_e32 v8, v125
	v_mov_b32_e32 v9, v125
	v_mov_b32_e32 v10, v125
	v_mov_b32_e32 v11, v125
	v_mov_b32_e32 v12, v125
	v_mov_b32_e32 v13, v125
	v_mov_b32_e32 v14, v125
	v_mov_b32_e32 v15, v125
	v_mov_b32_e32 v16, v125
	v_mov_b32_e32 v17, v125
	v_mov_b32_e32 v18, v125
	v_mov_b32_e32 v19, v125
	v_mov_b32_e32 v20, v125
	v_mov_b32_e32 v21, v125
	v_mov_b32_e32 v22, v125
	v_mov_b32_e32 v23, v125
	v_mov_b32_e32 v24, v125
	v_mov_b32_e32 v25, v125
	v_mov_b32_e32 v26, v125
	v_mov_b32_e32 v27, v125
	v_mov_b32_e32 v28, v125
	v_mov_b32_e32 v29, v125
	v_mov_b32_e32 v30, v125
	v_mov_b32_e32 v31, v125
	v_mov_b32_e32 v32, v125
	v_mov_b32_e32 v33, v125
	v_mov_b32_e32 v34, v125
	v_mov_b32_e32 v35, v125
	v_mov_b32_e32 v36, v125
	v_mov_b32_e32 v37, v125
	v_mov_b32_e32 v38, v125
	v_mov_b32_e32 v39, v125
	v_mov_b32_e32 v40, v125
	v_mov_b32_e32 v41, v125
	v_mov_b32_e32 v42, v125
	v_mov_b32_e32 v43, v125
	v_mov_b32_e32 v44, v125
	v_mov_b32_e32 v45, v125
	v_mov_b32_e32 v46, v125
	v_mov_b32_e32 v47, v125
	v_mov_b32_e32 v48, v125
	v_mov_b32_e32 v49, v125
	v_mov_b32_e32 v50, v125
	v_mov_b32_e32 v51, v125
	v_mov_b32_e32 v52, v125
	v_mov_b32_e32 v53, v125
	v_mov_b32_e32 v54, v125
	v_mov_b32_e32 v55, v125
	v_mov_b32_e32 v56, v125
	v_mov_b32_e32 v57, v125
	v_mov_b32_e32 v58, v125
	v_mov_b32_e32 v59, v125
	v_mov_b32_e32 v60, v125
	v_mov_b32_e32 v61, v125
	v_mov_b32_e32 v62, v125
	v_mov_b32_e32 v63, v125
	v_mov_b32_e32 v64, v125
	v_mov_b32_e32 v65, v125
	v_mov_b32_e32 v66, v125
	v_mov_b32_e32 v67, v125
	v_mov_b32_e32 v68, v125
	v_mov_b32_e32 v69, v125
	v_mov_b32_e32 v70, v125
	v_mov_b32_e32 v71, v125
	v_mov_b32_e32 v72, v125
	v_mov_b32_e32 v73, v125
	v_mov_b32_e32 v74, v125
	v_mov_b32_e32 v75, v125
	v_mov_b32_e32 v76, v125
	v_mov_b32_e32 v77, v125
	v_mov_b32_e32 v78, v125
	v_mov_b32_e32 v79, v125
	v_mov_b32_e32 v80, v125
	v_mov_b32_e32 v81, v125
	v_mov_b32_e32 v82, v125
	v_mov_b32_e32 v83, v125
	v_mov_b32_e32 v84, v125
	v_mov_b32_e32 v85, v125
	v_mov_b32_e32 v86, v125
	v_mov_b32_e32 v87, v125
	v_mov_b32_e32 v88, v125
	v_mov_b32_e32 v89, v125
	v_mov_b32_e32 v90, v125
	v_mov_b32_e32 v91, v125
	v_mov_b32_e32 v92, v125
	v_mov_b32_e32 v93, v125
	v_mov_b32_e32 v94, v125
	v_mov_b32_e32 v95, v125
	v_mov_b32_e32 v96, v125
	v_mov_b32_e32 v97, v125
	v_mov_b32_e32 v98, v125
	v_mov_b32_e32 v99, v125
	v_mov_b32_e32 v100, v125
	v_mov_b32_e32 v101, v125
	v_mov_b32_e32 v102, v125
	v_mov_b32_e32 v103, v125
	v_mov_b32_e32 v104, v125
	v_mov_b32_e32 v105, v125
	v_mov_b32_e32 v106, v125
	v_mov_b32_e32 v107, v125
	v_mov_b32_e32 v108, v125
	v_mov_b32_e32 v109, v125
	v_mov_b32_e32 v110, v125
	v_mov_b32_e32 v111, v125
	v_mov_b32_e32 v112, v125
	v_mov_b32_e32 v113, v125
	v_mov_b32_e32 v114, v125
	v_mov_b32_e32 v115, v125
	v_mov_b32_e32 v116, v125
	v_mov_b32_e32 v117, v125
	v_mov_b32_e32 v118, v125
	v_mov_b32_e32 v119, v125
	v_mov_b32_e32 v120, v125
	v_mov_b32_e32 v121, v125
	v_mov_b32_e32 v122, v125
	v_mov_b32_e32 v123, v125
	v_mov_b32_e32 v124, v125
	v_mov_b32_e32 v126, v125
	v_mov_b32_e32 v127, v125
	v_mov_b32_e32 v128, v125
	v_mov_b32_e32 v129, v125
	s_and_saveexec_b64 s[2:3], s[4:5]
	s_cbranch_execz .LBB0_398
	s_barrier
.LBB0_398:
	s_or_b64 exec, exec, s[2:3]
	s_waitcnt vmcnt(10)
	s_barrier
	s_andn2_b64 vcc, exec, s[20:21]
	s_waitcnt vmcnt(6)
	s_barrier
	s_cbranch_vccnz .LBB0_402
	s_add_u32 s0, s91, 0x80
	s_addc_u32 s1, s76, 0
	s_mul_i32 s1, s54, s1
	s_mul_hi_u32 s2, s54, s0
	s_add_i32 s1, s2, s1
	s_mul_i32 s2, s55, s0
	s_add_i32 s1, s1, s2
	s_mul_i32 s0, s54, s0
	s_add_u32 s0, s56, s0
	s_addc_u32 s1, s57, s1
	s_add_u32 s2, s74, 0x80
	s_addc_u32 s3, s77, 0
	s_mul_i32 s3, s54, s3
	s_mul_hi_u32 s56, s54, s2
	s_add_i32 s3, s56, s3
	s_mul_i32 s56, s55, s2
	s_add_i32 s3, s3, s56
	s_mul_i32 s2, s54, s2
	s_add_u32 s2, s14, s2
	s_addc_u32 s3, s15, s3
	s_mov_b32 s56, 0
	s_mov_b64 s[14:15], 0
